# GLA prep gate stage VALU diet: 16x48 f32 projection as packed FMAs (was fmac plus pk_mul and adds), logsigmoid without the identity denormal and infinity selects of logf since its argument lies in [1,
# speedup vs baseline: 1.0078x; 1.0078x over previous
.LBB0_592:
	v_cndmask_b32_e64 v72, v137, v134, s[64:65]
	s_movk_i32 s38, 0xd0
	v_mad_u32_u24 v72, v72, s38, v138
	s_waitcnt lgkmcnt(0)
	s_barrier
	ds_write_b128 v72, v[60:63] offset:48128
	v_cndmask_b32_e64 v72, v139, v133, s[64:65]
	v_mad_u32_u24 v72, v72, s38, v140
	ds_write_b128 v72, v[56:59] offset:48128
	v_cndmask_b32_e64 v72, v141, v132, s[64:65]
	v_mad_u32_u24 v72, v72, s38, v142
	ds_write_b128 v72, v[64:67] offset:48128
	v_cndmask_b32_e64 v0, v136, v135, s[64:65]
	s_waitcnt lgkmcnt(0)
	s_barrier
	v_cndmask_b32_e64 v3, v47, v55, s[64:65]
	v_cndmask_b32_e64 v2, v46, v54, s[64:65]
	v_cndmask_b32_e64 v68, v45, v53, s[64:65]
	v_cndmask_b32_e64 v69, v44, v52, s[64:65]
	v_cndmask_b32_e64 v75, v43, v51, s[64:65]
	v_cndmask_b32_e64 v73, v42, v50, s[64:65]
	v_cndmask_b32_e64 v71, v41, v49, s[64:65]
	v_cndmask_b32_e64 v70, v40, v48, s[64:65]
	v_mul_u32_u24_e32 v76, 49, v0
	s_mul_i32 s38, s73, 0xcc0
	s_xor_b64 s[62:63], s[64:65], -1
	v_lshlrev_b32_e32 v78, 16, v69
	v_and_b32_e32 v79, 0xffff0000, v69
	v_lshlrev_b32_e32 v80, 16, v68
	v_and_b32_e32 v81, 0xffff0000, v68
	v_lshlrev_b32_e32 v90, 16, v2
	v_and_b32_e32 v91, 0xffff0000, v2
	v_lshlrev_b32_e32 v2, 16, v3
	v_and_b32_e32 v3, 0xffff0000, v3
	v_lshlrev_b32_e32 v68, 16, v70
	v_and_b32_e32 v69, 0xffff0000, v70
	v_lshlrev_b32_e32 v70, 16, v71
	v_and_b32_e32 v71, 0xffff0000, v71
	v_lshlrev_b32_e32 v72, 16, v73
	v_and_b32_e32 v73, 0xffff0000, v73
	v_lshlrev_b32_e32 v74, 16, v75
	v_and_b32_e32 v75, 0xffff0000, v75
	v_add_u32_e32 v83, s38, v164
	v_lshl_add_u32 v84, v76, 2, v165
	s_mov_b32 s38, 0
.LBB0_593:
	ds_read_b128 v[196:199], v83 offset:3072
	ds_read_b128 v[234:237], v83 offset:0
	ds_read_b128 v[238:241], v83 offset:192
	ds_read_b128 v[242:245], v83 offset:384
	ds_read_b128 v[246:249], v83 offset:576
	ds_read_b128 v[250:253], v83 offset:768
	ds_read_b128 v[192:195], v83 offset:960
	ds_read_b128 v[200:203], v83 offset:1152
	ds_read_b128 v[86:89], v83 offset:1344
	s_waitcnt lgkmcnt(4)
	v_pk_fma_f32 v[196:197], v[234:235], v[78:79], v[196:197] op_sel_hi:[1,0,1]
	v_pk_fma_f32 v[198:199], v[236:237], v[78:79], v[198:199] op_sel_hi:[1,0,1]
	v_pk_fma_f32 v[196:197], v[238:239], v[78:79], v[196:197] op_sel:[0,1,0] op_sel_hi:[1,1,1]
	v_pk_fma_f32 v[198:199], v[240:241], v[78:79], v[198:199] op_sel:[0,1,0] op_sel_hi:[1,1,1]
	v_pk_fma_f32 v[196:197], v[242:243], v[80:81], v[196:197] op_sel_hi:[1,0,1]
	v_pk_fma_f32 v[198:199], v[244:245], v[80:81], v[198:199] op_sel_hi:[1,0,1]
	v_pk_fma_f32 v[196:197], v[246:247], v[80:81], v[196:197] op_sel:[0,1,0] op_sel_hi:[1,1,1]
	v_pk_fma_f32 v[198:199], v[248:249], v[80:81], v[198:199] op_sel:[0,1,0] op_sel_hi:[1,1,1]
	ds_read_b128 v[234:237], v83 offset:1536
	ds_read_b128 v[238:241], v83 offset:1728
	ds_read_b128 v[242:245], v83 offset:1920
	ds_read_b128 v[246:249], v83 offset:2112
	s_waitcnt lgkmcnt(4)
	v_pk_fma_f32 v[196:197], v[250:251], v[90:91], v[196:197] op_sel_hi:[1,0,1]
	v_pk_fma_f32 v[198:199], v[252:253], v[90:91], v[198:199] op_sel_hi:[1,0,1]
	v_pk_fma_f32 v[196:197], v[192:193], v[90:91], v[196:197] op_sel:[0,1,0] op_sel_hi:[1,1,1]
	v_pk_fma_f32 v[198:199], v[194:195], v[90:91], v[198:199] op_sel:[0,1,0] op_sel_hi:[1,1,1]
	v_pk_fma_f32 v[196:197], v[200:201], v[2:3], v[196:197] op_sel_hi:[1,0,1]
	v_pk_fma_f32 v[198:199], v[202:203], v[2:3], v[198:199] op_sel_hi:[1,0,1]
	v_pk_fma_f32 v[196:197], v[86:87], v[2:3], v[196:197] op_sel:[0,1,0] op_sel_hi:[1,1,1]
	v_pk_fma_f32 v[198:199], v[88:89], v[2:3], v[198:199] op_sel:[0,1,0] op_sel_hi:[1,1,1]
	ds_read_b128 v[250:253], v83 offset:2304
	ds_read_b128 v[192:195], v83 offset:2496
	ds_read_b128 v[200:203], v83 offset:2688
	ds_read_b128 v[86:89], v83 offset:2880
	s_waitcnt lgkmcnt(4)
	v_pk_fma_f32 v[196:197], v[234:235], v[68:69], v[196:197] op_sel_hi:[1,0,1]
	v_pk_fma_f32 v[198:199], v[236:237], v[68:69], v[198:199] op_sel_hi:[1,0,1]
	v_pk_fma_f32 v[196:197], v[238:239], v[68:69], v[196:197] op_sel:[0,1,0] op_sel_hi:[1,1,1]
	v_pk_fma_f32 v[198:199], v[240:241], v[68:69], v[198:199] op_sel:[0,1,0] op_sel_hi:[1,1,1]
	v_pk_fma_f32 v[196:197], v[242:243], v[70:71], v[196:197] op_sel_hi:[1,0,1]
	v_pk_fma_f32 v[198:199], v[244:245], v[70:71], v[198:199] op_sel_hi:[1,0,1]
	v_pk_fma_f32 v[196:197], v[246:247], v[70:71], v[196:197] op_sel:[0,1,0] op_sel_hi:[1,1,1]
	v_pk_fma_f32 v[198:199], v[248:249], v[70:71], v[198:199] op_sel:[0,1,0] op_sel_hi:[1,1,1]
	s_waitcnt lgkmcnt(0)
	v_pk_fma_f32 v[196:197], v[250:251], v[72:73], v[196:197] op_sel_hi:[1,0,1]
	v_pk_fma_f32 v[198:199], v[252:253], v[72:73], v[198:199] op_sel_hi:[1,0,1]
	v_pk_fma_f32 v[196:197], v[192:193], v[72:73], v[196:197] op_sel:[0,1,0] op_sel_hi:[1,1,1]
	v_pk_fma_f32 v[198:199], v[194:195], v[72:73], v[198:199] op_sel:[0,1,0] op_sel_hi:[1,1,1]
	v_pk_fma_f32 v[196:197], v[200:201], v[74:75], v[196:197] op_sel_hi:[1,0,1]
	v_pk_fma_f32 v[198:199], v[202:203], v[74:75], v[198:199] op_sel_hi:[1,0,1]
	v_pk_fma_f32 v[196:197], v[86:87], v[74:75], v[196:197] op_sel:[0,1,0] op_sel_hi:[1,1,1]
	v_pk_fma_f32 v[198:199], v[88:89], v[74:75], v[198:199] op_sel:[0,1,0] op_sel_hi:[1,1,1]
	v_min_f32_e32 v85, 0, v196
	v_min_f32_e32 v191, 0, v197
	v_min_f32_e32 v107, 0, v198
	v_min_f32_e32 v233, 0, v199
	v_mul_f32_e64 v196, |v196|, s36
	v_mul_f32_e64 v197, |v197|, s36
	v_mul_f32_e64 v198, |v198|, s36
	v_mul_f32_e64 v199, |v199|, s36
	v_exp_f32_e32 v196, v196
	v_exp_f32_e32 v197, v197
	v_exp_f32_e32 v198, v198
	v_exp_f32_e32 v199, v199
	s_nop 0
	v_add_f32_e32 v196, 1.0, v196
	v_add_f32_e32 v197, 1.0, v197
	v_add_f32_e32 v198, 1.0, v198
	v_add_f32_e32 v199, 1.0, v199
	v_log_f32_e32 v196, v196
	v_log_f32_e32 v197, v197
	v_log_f32_e32 v198, v198
	v_log_f32_e32 v199, v199
	s_nop 0
	v_mul_f32_e32 v121, 0x3f317217, v196
	v_mul_f32_e32 v205, 0x3f317217, v197
	v_mul_f32_e32 v204, 0x3f317217, v198
	v_mul_f32_e32 v77, 0x3f317217, v199
	v_fma_f32 v121, v196, s75, -v121
	v_fma_f32 v205, v197, s75, -v205
	v_fma_f32 v204, v198, s75, -v204
	v_fma_f32 v77, v199, s75, -v77
	v_fmac_f32_e32 v121, 0x3377d1cf, v196
	v_fmac_f32_e32 v205, 0x3377d1cf, v197
	v_fmac_f32_e32 v204, 0x3377d1cf, v198
	v_fmac_f32_e32 v77, 0x3377d1cf, v199
	v_fmac_f32_e32 v121, 0x3f317217, v196
	v_fmac_f32_e32 v205, 0x3f317217, v197
	v_fmac_f32_e32 v204, 0x3f317217, v198
	v_fmac_f32_e32 v77, 0x3f317217, v199
	v_sub_f32_e32 v196, v85, v121
	v_sub_f32_e32 v197, v191, v205
	v_sub_f32_e32 v198, v107, v204
	v_sub_f32_e32 v199, v233, v77
	v_mul_f32_e32 v196, 0x3d800000, v196
	v_mul_f32_e32 v197, 0x3d800000, v197
	v_mul_f32_e32 v198, 0x3d800000, v198
	v_mul_f32_e32 v199, 0x3d800000, v199
	ds_write_b32 v84, v196
	ds_write_b32 v84, v197 offset:4
	ds_write_b32 v84, v198 offset:8
	ds_write_b32 v84, v199 offset:12
	ds_read_b128 v[196:199], v83 offset:3088
	ds_read_b128 v[234:237], v83 offset:16
	ds_read_b128 v[238:241], v83 offset:208
	ds_read_b128 v[242:245], v83 offset:400
	ds_read_b128 v[246:249], v83 offset:592
	ds_read_b128 v[250:253], v83 offset:784
	ds_read_b128 v[192:195], v83 offset:976
	ds_read_b128 v[200:203], v83 offset:1168
	ds_read_b128 v[86:89], v83 offset:1360
	s_waitcnt lgkmcnt(4)
	v_pk_fma_f32 v[196:197], v[234:235], v[78:79], v[196:197] op_sel_hi:[1,0,1]
	v_pk_fma_f32 v[198:199], v[236:237], v[78:79], v[198:199] op_sel_hi:[1,0,1]
	v_pk_fma_f32 v[196:197], v[238:239], v[78:79], v[196:197] op_sel:[0,1,0] op_sel_hi:[1,1,1]
	v_pk_fma_f32 v[198:199], v[240:241], v[78:79], v[198:199] op_sel:[0,1,0] op_sel_hi:[1,1,1]
	v_pk_fma_f32 v[196:197], v[242:243], v[80:81], v[196:197] op_sel_hi:[1,0,1]
	v_pk_fma_f32 v[198:199], v[244:245], v[80:81], v[198:199] op_sel_hi:[1,0,1]
	v_pk_fma_f32 v[196:197], v[246:247], v[80:81], v[196:197] op_sel:[0,1,0] op_sel_hi:[1,1,1]
	v_pk_fma_f32 v[198:199], v[248:249], v[80:81], v[198:199] op_sel:[0,1,0] op_sel_hi:[1,1,1]
	ds_read_b128 v[234:237], v83 offset:1552
	ds_read_b128 v[238:241], v83 offset:1744
	ds_read_b128 v[242:245], v83 offset:1936
	ds_read_b128 v[246:249], v83 offset:2128
	s_waitcnt lgkmcnt(4)
	v_pk_fma_f32 v[196:197], v[250:251], v[90:91], v[196:197] op_sel_hi:[1,0,1]
	v_pk_fma_f32 v[198:199], v[252:253], v[90:91], v[198:199] op_sel_hi:[1,0,1]
	v_pk_fma_f32 v[196:197], v[192:193], v[90:91], v[196:197] op_sel:[0,1,0] op_sel_hi:[1,1,1]
	v_pk_fma_f32 v[198:199], v[194:195], v[90:91], v[198:199] op_sel:[0,1,0] op_sel_hi:[1,1,1]
	v_pk_fma_f32 v[196:197], v[200:201], v[2:3], v[196:197] op_sel_hi:[1,0,1]
	v_pk_fma_f32 v[198:199], v[202:203], v[2:3], v[198:199] op_sel_hi:[1,0,1]
	v_pk_fma_f32 v[196:197], v[86:87], v[2:3], v[196:197] op_sel:[0,1,0] op_sel_hi:[1,1,1]
	v_pk_fma_f32 v[198:199], v[88:89], v[2:3], v[198:199] op_sel:[0,1,0] op_sel_hi:[1,1,1]
	ds_read_b128 v[250:253], v83 offset:2320
	ds_read_b128 v[192:195], v83 offset:2512
	ds_read_b128 v[200:203], v83 offset:2704
	ds_read_b128 v[86:89], v83 offset:2896
	s_waitcnt lgkmcnt(4)
	v_pk_fma_f32 v[196:197], v[234:235], v[68:69], v[196:197] op_sel_hi:[1,0,1]
	v_pk_fma_f32 v[198:199], v[236:237], v[68:69], v[198:199] op_sel_hi:[1,0,1]
	v_pk_fma_f32 v[196:197], v[238:239], v[68:69], v[196:197] op_sel:[0,1,0] op_sel_hi:[1,1,1]
	v_pk_fma_f32 v[198:199], v[240:241], v[68:69], v[198:199] op_sel:[0,1,0] op_sel_hi:[1,1,1]
	v_pk_fma_f32 v[196:197], v[242:243], v[70:71], v[196:197] op_sel_hi:[1,0,1]
	v_pk_fma_f32 v[198:199], v[244:245], v[70:71], v[198:199] op_sel_hi:[1,0,1]
	v_pk_fma_f32 v[196:197], v[246:247], v[70:71], v[196:197] op_sel:[0,1,0] op_sel_hi:[1,1,1]
	v_pk_fma_f32 v[198:199], v[248:249], v[70:71], v[198:199] op_sel:[0,1,0] op_sel_hi:[1,1,1]
	s_waitcnt lgkmcnt(0)
	v_pk_fma_f32 v[196:197], v[250:251], v[72:73], v[196:197] op_sel_hi:[1,0,1]
	v_pk_fma_f32 v[198:199], v[252:253], v[72:73], v[198:199] op_sel_hi:[1,0,1]
	v_pk_fma_f32 v[196:197], v[192:193], v[72:73], v[196:197] op_sel:[0,1,0] op_sel_hi:[1,1,1]
	v_pk_fma_f32 v[198:199], v[194:195], v[72:73], v[198:199] op_sel:[0,1,0] op_sel_hi:[1,1,1]
	v_pk_fma_f32 v[196:197], v[200:201], v[74:75], v[196:197] op_sel_hi:[1,0,1]
	v_pk_fma_f32 v[198:199], v[202:203], v[74:75], v[198:199] op_sel_hi:[1,0,1]
	v_pk_fma_f32 v[196:197], v[86:87], v[74:75], v[196:197] op_sel:[0,1,0] op_sel_hi:[1,1,1]
	v_pk_fma_f32 v[198:199], v[88:89], v[74:75], v[198:199] op_sel:[0,1,0] op_sel_hi:[1,1,1]
	v_min_f32_e32 v85, 0, v196
	v_min_f32_e32 v191, 0, v197
	v_min_f32_e32 v107, 0, v198
	v_min_f32_e32 v233, 0, v199
	v_mul_f32_e64 v196, |v196|, s36
	v_mul_f32_e64 v197, |v197|, s36
	v_mul_f32_e64 v198, |v198|, s36
	v_mul_f32_e64 v199, |v199|, s36
	v_exp_f32_e32 v196, v196
	v_exp_f32_e32 v197, v197
	v_exp_f32_e32 v198, v198
	v_exp_f32_e32 v199, v199
	s_nop 0
	v_add_f32_e32 v196, 1.0, v196
	v_add_f32_e32 v197, 1.0, v197
	v_add_f32_e32 v198, 1.0, v198
	v_add_f32_e32 v199, 1.0, v199
	v_log_f32_e32 v196, v196
	v_log_f32_e32 v197, v197
	v_log_f32_e32 v198, v198
	v_log_f32_e32 v199, v199
	s_nop 0
	v_mul_f32_e32 v121, 0x3f317217, v196
	v_mul_f32_e32 v205, 0x3f317217, v197
	v_mul_f32_e32 v204, 0x3f317217, v198
	v_mul_f32_e32 v77, 0x3f317217, v199
	v_fma_f32 v121, v196, s75, -v121
	v_fma_f32 v205, v197, s75, -v205
	v_fma_f32 v204, v198, s75, -v204
	v_fma_f32 v77, v199, s75, -v77
	v_fmac_f32_e32 v121, 0x3377d1cf, v196
	v_fmac_f32_e32 v205, 0x3377d1cf, v197
	v_fmac_f32_e32 v204, 0x3377d1cf, v198
	v_fmac_f32_e32 v77, 0x3377d1cf, v199
	v_fmac_f32_e32 v121, 0x3f317217, v196
	v_fmac_f32_e32 v205, 0x3f317217, v197
	v_fmac_f32_e32 v204, 0x3f317217, v198
	v_fmac_f32_e32 v77, 0x3f317217, v199
	v_sub_f32_e32 v196, v85, v121
	v_sub_f32_e32 v197, v191, v205
	v_sub_f32_e32 v198, v107, v204
	v_sub_f32_e32 v199, v233, v77
	v_mul_f32_e32 v196, 0x3d800000, v196
	v_mul_f32_e32 v197, 0x3d800000, v197
	v_mul_f32_e32 v198, 0x3d800000, v198
	v_mul_f32_e32 v199, 0x3d800000, v199
	ds_write_b32 v84, v196 offset:16
	ds_write_b32 v84, v197 offset:20
	ds_write_b32 v84, v198 offset:24
	ds_write_b32 v84, v199 offset:28
	ds_read_b128 v[196:199], v83 offset:3104
	ds_read_b128 v[234:237], v83 offset:32
	ds_read_b128 v[238:241], v83 offset:224
	ds_read_b128 v[242:245], v83 offset:416
	ds_read_b128 v[246:249], v83 offset:608
	ds_read_b128 v[250:253], v83 offset:800
	ds_read_b128 v[192:195], v83 offset:992
	ds_read_b128 v[200:203], v83 offset:1184
	ds_read_b128 v[86:89], v83 offset:1376
	s_waitcnt lgkmcnt(4)
	v_pk_fma_f32 v[196:197], v[234:235], v[78:79], v[196:197] op_sel_hi:[1,0,1]
	v_pk_fma_f32 v[198:199], v[236:237], v[78:79], v[198:199] op_sel_hi:[1,0,1]
	v_pk_fma_f32 v[196:197], v[238:239], v[78:79], v[196:197] op_sel:[0,1,0] op_sel_hi:[1,1,1]
	v_pk_fma_f32 v[198:199], v[240:241], v[78:79], v[198:199] op_sel:[0,1,0] op_sel_hi:[1,1,1]
	v_pk_fma_f32 v[196:197], v[242:243], v[80:81], v[196:197] op_sel_hi:[1,0,1]
	v_pk_fma_f32 v[198:199], v[244:245], v[80:81], v[198:199] op_sel_hi:[1,0,1]
	v_pk_fma_f32 v[196:197], v[246:247], v[80:81], v[196:197] op_sel:[0,1,0] op_sel_hi:[1,1,1]
	v_pk_fma_f32 v[198:199], v[248:249], v[80:81], v[198:199] op_sel:[0,1,0] op_sel_hi:[1,1,1]
	ds_read_b128 v[234:237], v83 offset:1568
	ds_read_b128 v[238:241], v83 offset:1760
	ds_read_b128 v[242:245], v83 offset:1952
	ds_read_b128 v[246:249], v83 offset:2144
	s_waitcnt lgkmcnt(4)
	v_pk_fma_f32 v[196:197], v[250:251], v[90:91], v[196:197] op_sel_hi:[1,0,1]
	v_pk_fma_f32 v[198:199], v[252:253], v[90:91], v[198:199] op_sel_hi:[1,0,1]
	v_pk_fma_f32 v[196:197], v[192:193], v[90:91], v[196:197] op_sel:[0,1,0] op_sel_hi:[1,1,1]
	v_pk_fma_f32 v[198:199], v[194:195], v[90:91], v[198:199] op_sel:[0,1,0] op_sel_hi:[1,1,1]
	v_pk_fma_f32 v[196:197], v[200:201], v[2:3], v[196:197] op_sel_hi:[1,0,1]
	v_pk_fma_f32 v[198:199], v[202:203], v[2:3], v[198:199] op_sel_hi:[1,0,1]
	v_pk_fma_f32 v[196:197], v[86:87], v[2:3], v[196:197] op_sel:[0,1,0] op_sel_hi:[1,1,1]
	v_pk_fma_f32 v[198:199], v[88:89], v[2:3], v[198:199] op_sel:[0,1,0] op_sel_hi:[1,1,1]
	ds_read_b128 v[250:253], v83 offset:2336
	ds_read_b128 v[192:195], v83 offset:2528
	ds_read_b128 v[200:203], v83 offset:2720
	ds_read_b128 v[86:89], v83 offset:2912
	s_waitcnt lgkmcnt(4)
	v_pk_fma_f32 v[196:197], v[234:235], v[68:69], v[196:197] op_sel_hi:[1,0,1]
	v_pk_fma_f32 v[198:199], v[236:237], v[68:69], v[198:199] op_sel_hi:[1,0,1]
	v_pk_fma_f32 v[196:197], v[238:239], v[68:69], v[196:197] op_sel:[0,1,0] op_sel_hi:[1,1,1]
	v_pk_fma_f32 v[198:199], v[240:241], v[68:69], v[198:199] op_sel:[0,1,0] op_sel_hi:[1,1,1]
	v_pk_fma_f32 v[196:197], v[242:243], v[70:71], v[196:197] op_sel_hi:[1,0,1]
	v_pk_fma_f32 v[198:199], v[244:245], v[70:71], v[198:199] op_sel_hi:[1,0,1]
	v_pk_fma_f32 v[196:197], v[246:247], v[70:71], v[196:197] op_sel:[0,1,0] op_sel_hi:[1,1,1]
	v_pk_fma_f32 v[198:199], v[248:249], v[70:71], v[198:199] op_sel:[0,1,0] op_sel_hi:[1,1,1]
	s_waitcnt lgkmcnt(0)
	v_pk_fma_f32 v[196:197], v[250:251], v[72:73], v[196:197] op_sel_hi:[1,0,1]
	v_pk_fma_f32 v[198:199], v[252:253], v[72:73], v[198:199] op_sel_hi:[1,0,1]
	v_pk_fma_f32 v[196:197], v[192:193], v[72:73], v[196:197] op_sel:[0,1,0] op_sel_hi:[1,1,1]
	v_pk_fma_f32 v[198:199], v[194:195], v[72:73], v[198:199] op_sel:[0,1,0] op_sel_hi:[1,1,1]
	v_pk_fma_f32 v[196:197], v[200:201], v[74:75], v[196:197] op_sel_hi:[1,0,1]
	v_pk_fma_f32 v[198:199], v[202:203], v[74:75], v[198:199] op_sel_hi:[1,0,1]
	v_pk_fma_f32 v[196:197], v[86:87], v[74:75], v[196:197] op_sel:[0,1,0] op_sel_hi:[1,1,1]
	v_pk_fma_f32 v[198:199], v[88:89], v[74:75], v[198:199] op_sel:[0,1,0] op_sel_hi:[1,1,1]
	v_min_f32_e32 v85, 0, v196
	v_min_f32_e32 v191, 0, v197
	v_min_f32_e32 v107, 0, v198
	v_min_f32_e32 v233, 0, v199
	v_mul_f32_e64 v196, |v196|, s36
	v_mul_f32_e64 v197, |v197|, s36
	v_mul_f32_e64 v198, |v198|, s36
	v_mul_f32_e64 v199, |v199|, s36
	v_exp_f32_e32 v196, v196
	v_exp_f32_e32 v197, v197
	v_exp_f32_e32 v198, v198
	v_exp_f32_e32 v199, v199
	s_nop 0
	v_add_f32_e32 v196, 1.0, v196
	v_add_f32_e32 v197, 1.0, v197
	v_add_f32_e32 v198, 1.0, v198
	v_add_f32_e32 v199, 1.0, v199
	v_log_f32_e32 v196, v196
	v_log_f32_e32 v197, v197
	v_log_f32_e32 v198, v198
	v_log_f32_e32 v199, v199
	s_nop 0
	v_mul_f32_e32 v121, 0x3f317217, v196
	v_mul_f32_e32 v205, 0x3f317217, v197
	v_mul_f32_e32 v204, 0x3f317217, v198
	v_mul_f32_e32 v77, 0x3f317217, v199
	v_fma_f32 v121, v196, s75, -v121
	v_fma_f32 v205, v197, s75, -v205
	v_fma_f32 v204, v198, s75, -v204
	v_fma_f32 v77, v199, s75, -v77
	v_fmac_f32_e32 v121, 0x3377d1cf, v196
	v_fmac_f32_e32 v205, 0x3377d1cf, v197
	v_fmac_f32_e32 v204, 0x3377d1cf, v198
	v_fmac_f32_e32 v77, 0x3377d1cf, v199
	v_fmac_f32_e32 v121, 0x3f317217, v196
	v_fmac_f32_e32 v205, 0x3f317217, v197
	v_fmac_f32_e32 v204, 0x3f317217, v198
	v_fmac_f32_e32 v77, 0x3f317217, v199
	v_sub_f32_e32 v196, v85, v121
	v_sub_f32_e32 v197, v191, v205
	v_sub_f32_e32 v198, v107, v204
	v_sub_f32_e32 v199, v233, v77
	v_mul_f32_e32 v196, 0x3d800000, v196
	v_mul_f32_e32 v197, 0x3d800000, v197
	v_mul_f32_e32 v198, 0x3d800000, v198
	v_mul_f32_e32 v199, 0x3d800000, v199
	ds_write_b32 v84, v196 offset:32
	ds_write_b32 v84, v197 offset:36
	ds_write_b32 v84, v198 offset:40
	ds_write_b32 v84, v199 offset:44
	s_waitcnt lgkmcnt(0)
	s_barrier
	s_and_saveexec_b64 s[68:69], s[48:49]
	s_cbranch_execz .LBB0_598
	v_mov_b32_e32 v2, 0
	s_mov_b32 s38, 0
